# phase0 adaLN w_mod dot loop: 4 k-blocks (32 loads) in flight with counted vmcnt instead of one k-block per round trip
# baseline (speedup 1.0000x reference)
; DI void phase0(const Params& p, unsigned char* smem, int bid, int nb) {
;     ...
;       const int kg = tid >> 6, j = tid & 63;
;       float a0 = 0.f, a1 = 0.f, a2 = 0.f;
;       const float* wp = p.w_mod + ((size_t)l * 1024 + kg * 256) * 6144 + col0 + j;
; #pragma unroll 8
;       for (int k = 0; k < 256; ++k) {
;         const float w = wp[(size_t)k * 6144];
;         a0 += sc[kg * 256 + k] * w; a1 += sc[1024 + kg * 256 + k] * w; a2 += sc[2048 + kg * 256 + k] * w;
.LBB0_39:
	s_or_b64 exec, exec, s[54:55]
	s_mul_hi_i32 s16, s83, 0x2aaaaaab
	s_lshr_b32 s17, s16, 31
	s_ashr_i32 s16, s16, 4
	s_add_i32 s16, s16, s17
	s_mul_i32 s17, s16, 0x60
	s_sub_i32 s17, s83, s17
	s_lshl_b32 s18, s17, 6
	s_ashr_i32 s17, s16, 31
	s_lshl_b64 s[20:21], s[16:17], 10
	v_lshl_add_u64 v[18:19], s[20:21], 0, v[10:11]
	v_mov_b64_e32 v[20:21], s[38:39]
	v_mad_u64_u32 v[20:21], s[20:21], v18, s76, v[20:21]
	v_mad_i32_i24 v21, v19, s76, v21
	s_ashr_i32 s19, s18, 31
	v_lshl_add_u64 v[18:19], s[18:19], 2, v[20:21]
	v_mov_b32_e32 v17, v5
	v_mov_b32_e32 v4, 0
	v_lshl_add_u64 v[18:19], v[18:19], 0, v[16:17]
	s_mov_b64 s[20:21], 0
	v_mov_b32_e32 v13, v31
	v_mov_b32_e32 v20, 0
	v_mov_b32_e32 v21, v4
	s_waitcnt lgkmcnt(0)
	s_barrier
	s_mov_b32 s22, 0
	s_mov_b32 s23, 0
	s_mov_b32 s17, 0
	v_lshl_add_u64 v[40:41], v[18:19], 0, s[22:23]
	global_load_dword v64, v[40:41], off
	v_add_co_u32_e32 v42, vcc, s76, v40
	s_nop 1
	v_addc_co_u32_e32 v43, vcc, 0, v41, vcc
	global_load_dword v66, v[42:43], off
	v_add_co_u32_e32 v42, vcc, s77, v40
	s_nop 1
	v_addc_co_u32_e32 v43, vcc, 0, v41, vcc
	global_load_dword v68, v[42:43], off
	v_add_co_u32_e32 v42, vcc, s63, v40
	s_nop 1
	v_addc_co_u32_e32 v43, vcc, 0, v41, vcc
	global_load_dword v70, v[42:43], off
	v_add_co_u32_e32 v42, vcc, s78, v40
	s_nop 1
	v_addc_co_u32_e32 v43, vcc, 0, v41, vcc
	global_load_dword v72, v[42:43], off
	v_add_co_u32_e32 v42, vcc, s79, v40
	s_nop 1
	v_addc_co_u32_e32 v43, vcc, 0, v41, vcc
	global_load_dword v74, v[42:43], off
	v_add_co_u32_e32 v42, vcc, s80, v40
	s_nop 1
	v_addc_co_u32_e32 v43, vcc, 0, v41, vcc
	global_load_dword v76, v[42:43], off
	v_add_co_u32_e32 v42, vcc, s81, v40
	s_nop 1
	v_addc_co_u32_e32 v43, vcc, 0, v41, vcc
	global_load_dword v78, v[42:43], off
	s_add_u32 s22, s22, 0x30000
	s_cmp_lg_u32 s22, 0x600000
	s_cselect_b32 s22, s22, 0
	v_lshl_add_u64 v[40:41], v[18:19], 0, s[22:23]
	global_load_dword v82, v[40:41], off
	v_add_co_u32_e32 v42, vcc, s76, v40
	s_nop 1
	v_addc_co_u32_e32 v43, vcc, 0, v41, vcc
	global_load_dword v84, v[42:43], off
	v_add_co_u32_e32 v42, vcc, s77, v40
	s_nop 1
	v_addc_co_u32_e32 v43, vcc, 0, v41, vcc
	global_load_dword v86, v[42:43], off
	v_add_co_u32_e32 v42, vcc, s63, v40
	s_nop 1
	v_addc_co_u32_e32 v43, vcc, 0, v41, vcc
	global_load_dword v88, v[42:43], off
	v_add_co_u32_e32 v42, vcc, s78, v40
	s_nop 1
	v_addc_co_u32_e32 v43, vcc, 0, v41, vcc
	global_load_dword v90, v[42:43], off
	v_add_co_u32_e32 v42, vcc, s79, v40
	s_nop 1
	v_addc_co_u32_e32 v43, vcc, 0, v41, vcc
	global_load_dword v92, v[42:43], off
	v_add_co_u32_e32 v42, vcc, s80, v40
	s_nop 1
	v_addc_co_u32_e32 v43, vcc, 0, v41, vcc
	global_load_dword v94, v[42:43], off
	v_add_co_u32_e32 v42, vcc, s81, v40
	s_nop 1
	v_addc_co_u32_e32 v43, vcc, 0, v41, vcc
	global_load_dword v96, v[42:43], off
	s_add_u32 s22, s22, 0x30000
	s_cmp_lg_u32 s22, 0x600000
	s_cselect_b32 s22, s22, 0
	v_lshl_add_u64 v[40:41], v[18:19], 0, s[22:23]
	global_load_dword v100, v[40:41], off
	v_add_co_u32_e32 v42, vcc, s76, v40
	s_nop 1
	v_addc_co_u32_e32 v43, vcc, 0, v41, vcc
	global_load_dword v102, v[42:43], off
	v_add_co_u32_e32 v42, vcc, s77, v40
	s_nop 1
	v_addc_co_u32_e32 v43, vcc, 0, v41, vcc
	global_load_dword v104, v[42:43], off
	v_add_co_u32_e32 v42, vcc, s63, v40
	s_nop 1
	v_addc_co_u32_e32 v43, vcc, 0, v41, vcc
	global_load_dword v106, v[42:43], off
	v_add_co_u32_e32 v42, vcc, s78, v40
	s_nop 1
	v_addc_co_u32_e32 v43, vcc, 0, v41, vcc
	global_load_dword v108, v[42:43], off
	v_add_co_u32_e32 v42, vcc, s79, v40
	s_nop 1
	v_addc_co_u32_e32 v43, vcc, 0, v41, vcc
	global_load_dword v110, v[42:43], off
	v_add_co_u32_e32 v42, vcc, s80, v40
	s_nop 1
	v_addc_co_u32_e32 v43, vcc, 0, v41, vcc
	global_load_dword v112, v[42:43], off
	v_add_co_u32_e32 v42, vcc, s81, v40
	s_nop 1
	v_addc_co_u32_e32 v43, vcc, 0, v41, vcc
	global_load_dword v114, v[42:43], off
	s_add_u32 s22, s22, 0x30000
	s_cmp_lg_u32 s22, 0x600000
	s_cselect_b32 s22, s22, 0
.LBB0_40:
	v_lshl_add_u64 v[40:41], v[18:19], 0, s[22:23]
	global_load_dword v118, v[40:41], off
	v_add_co_u32_e32 v42, vcc, s76, v40
	s_nop 1
	v_addc_co_u32_e32 v43, vcc, 0, v41, vcc
	global_load_dword v120, v[42:43], off
	v_add_co_u32_e32 v42, vcc, s77, v40
	s_nop 1
	v_addc_co_u32_e32 v43, vcc, 0, v41, vcc
	global_load_dword v122, v[42:43], off
	v_add_co_u32_e32 v42, vcc, s63, v40
	s_nop 1
	v_addc_co_u32_e32 v43, vcc, 0, v41, vcc
	global_load_dword v124, v[42:43], off
	v_add_co_u32_e32 v42, vcc, s78, v40
	s_nop 1
	v_addc_co_u32_e32 v43, vcc, 0, v41, vcc
	global_load_dword v126, v[42:43], off
	v_add_co_u32_e32 v42, vcc, s79, v40
	s_nop 1
	v_addc_co_u32_e32 v43, vcc, 0, v41, vcc
	global_load_dword v128, v[42:43], off
	v_add_co_u32_e32 v42, vcc, s80, v40
	s_nop 1
	v_addc_co_u32_e32 v43, vcc, 0, v41, vcc
	global_load_dword v130, v[42:43], off
	v_add_co_u32_e32 v42, vcc, s81, v40
	s_nop 1
	v_addc_co_u32_e32 v43, vcc, 0, v41, vcc
	global_load_dword v132, v[42:43], off
	s_add_u32 s22, s22, 0x30000
	s_cmp_lg_u32 s22, 0x600000
	s_cselect_b32 s22, s22, 0
	ds_read_b128 v[40:43], v13
	ds_read_b128 v[44:47], v13 offset:16
	ds_read_b128 v[48:51], v13 offset:4096
	ds_read_b128 v[52:55], v13 offset:4112
	ds_read_b128 v[56:59], v13 offset:8192
	ds_read_b128 v[60:63], v13 offset:8208
	s_waitcnt lgkmcnt(5)
	v_mov_b32_e32 v80, v40
	s_waitcnt lgkmcnt(3)
	v_mov_b32_e32 v81, v48
	v_mov_b32_e32 v48, v41
	v_mov_b32_e32 v40, v42
	v_mov_b32_e32 v41, v50
	v_mov_b32_e32 v50, v43
	v_mov_b32_e32 v42, v44
	s_waitcnt lgkmcnt(2)
	v_mov_b32_e32 v43, v52
	v_mov_b32_e32 v52, v45
	v_mov_b32_e32 v44, v46
	v_mov_b32_e32 v45, v54
	v_mov_b32_e32 v54, v47
	v_add_u32_e32 v13, 32, v13
	s_waitcnt vmcnt(31)
; DI void phase0(const Params& p, unsigned char* smem, int bid, int nb) {
;     ...
; #pragma unroll 8
;       for (int k = 0; k < 256; ++k) {
;         const float w = wp[(size_t)k * 6144];
;         a0 += sc[kg * 256 + k] * w; a1 += sc[1024 + kg * 256 + k] * w; a2 += sc[2048 + kg * 256 + k] * w;
	v_pk_fma_f32 v[20:21], v[64:65], v[80:81], v[20:21] op_sel_hi:[0,1,1]
	s_waitcnt lgkmcnt(1)
	v_fmac_f32_e32 v4, v64, v56
	s_waitcnt vmcnt(30)
	v_pk_fma_f32 v[20:21], v[66:67], v[48:49], v[20:21] op_sel_hi:[0,1,1]
	v_fmac_f32_e32 v4, v66, v57
	s_waitcnt vmcnt(29)
	v_pk_fma_f32 v[20:21], v[68:69], v[40:41], v[20:21] op_sel_hi:[0,1,1]
	v_fmac_f32_e32 v4, v68, v58
	s_waitcnt vmcnt(28)
	v_pk_fma_f32 v[20:21], v[70:71], v[50:51], v[20:21] op_sel_hi:[0,1,1]
	v_fmac_f32_e32 v4, v70, v59
	s_waitcnt vmcnt(27)
	v_pk_fma_f32 v[20:21], v[72:73], v[42:43], v[20:21] op_sel_hi:[0,1,1]
	s_waitcnt lgkmcnt(0)
	v_fmac_f32_e32 v4, v72, v60
	s_waitcnt vmcnt(26)
	v_pk_fma_f32 v[20:21], v[74:75], v[52:53], v[20:21] op_sel_hi:[0,1,1]
	v_fmac_f32_e32 v4, v74, v61
	s_waitcnt vmcnt(25)
	v_pk_fma_f32 v[20:21], v[76:77], v[44:45], v[20:21] op_sel_hi:[0,1,1]
	v_fmac_f32_e32 v4, v76, v62
	s_waitcnt vmcnt(24)
	v_pk_fma_f32 v[20:21], v[78:79], v[54:55], v[20:21] op_sel_hi:[0,1,1]
	v_fmac_f32_e32 v4, v78, v63
	v_lshl_add_u64 v[40:41], v[18:19], 0, s[22:23]
	global_load_dword v64, v[40:41], off
	v_add_co_u32_e32 v42, vcc, s76, v40
	s_nop 1
	v_addc_co_u32_e32 v43, vcc, 0, v41, vcc
	global_load_dword v66, v[42:43], off
	v_add_co_u32_e32 v42, vcc, s77, v40
	s_nop 1
	v_addc_co_u32_e32 v43, vcc, 0, v41, vcc
	global_load_dword v68, v[42:43], off
	v_add_co_u32_e32 v42, vcc, s63, v40
	s_nop 1
	v_addc_co_u32_e32 v43, vcc, 0, v41, vcc
	global_load_dword v70, v[42:43], off
	v_add_co_u32_e32 v42, vcc, s78, v40
	s_nop 1
	v_addc_co_u32_e32 v43, vcc, 0, v41, vcc
	global_load_dword v72, v[42:43], off
	v_add_co_u32_e32 v42, vcc, s79, v40
	s_nop 1
	v_addc_co_u32_e32 v43, vcc, 0, v41, vcc
	global_load_dword v74, v[42:43], off
	v_add_co_u32_e32 v42, vcc, s80, v40
	s_nop 1
	v_addc_co_u32_e32 v43, vcc, 0, v41, vcc
	global_load_dword v76, v[42:43], off
	v_add_co_u32_e32 v42, vcc, s81, v40
	s_nop 1
	v_addc_co_u32_e32 v43, vcc, 0, v41, vcc
	global_load_dword v78, v[42:43], off
	s_add_u32 s22, s22, 0x30000
	s_cmp_lg_u32 s22, 0x600000
	s_cselect_b32 s22, s22, 0
	ds_read_b128 v[40:43], v13
	ds_read_b128 v[44:47], v13 offset:16
	ds_read_b128 v[48:51], v13 offset:4096
	ds_read_b128 v[52:55], v13 offset:4112
	ds_read_b128 v[56:59], v13 offset:8192
	ds_read_b128 v[60:63], v13 offset:8208
	s_waitcnt lgkmcnt(5)
	v_mov_b32_e32 v80, v40
	s_waitcnt lgkmcnt(3)
	v_mov_b32_e32 v81, v48
	v_mov_b32_e32 v48, v41
	v_mov_b32_e32 v40, v42
	v_mov_b32_e32 v41, v50
	v_mov_b32_e32 v50, v43
	v_mov_b32_e32 v42, v44
	s_waitcnt lgkmcnt(2)
	v_mov_b32_e32 v43, v52
	v_mov_b32_e32 v52, v45
	v_mov_b32_e32 v44, v46
	v_mov_b32_e32 v45, v54
	v_mov_b32_e32 v54, v47
	v_add_u32_e32 v13, 32, v13
	s_waitcnt vmcnt(31)
	v_pk_fma_f32 v[20:21], v[82:83], v[80:81], v[20:21] op_sel_hi:[0,1,1]
	s_waitcnt lgkmcnt(1)
	v_fmac_f32_e32 v4, v82, v56
	s_waitcnt vmcnt(30)
	v_pk_fma_f32 v[20:21], v[84:85], v[48:49], v[20:21] op_sel_hi:[0,1,1]
	v_fmac_f32_e32 v4, v84, v57
	s_waitcnt vmcnt(29)
	v_pk_fma_f32 v[20:21], v[86:87], v[40:41], v[20:21] op_sel_hi:[0,1,1]
	v_fmac_f32_e32 v4, v86, v58
	s_waitcnt vmcnt(28)
	v_pk_fma_f32 v[20:21], v[88:89], v[50:51], v[20:21] op_sel_hi:[0,1,1]
	v_fmac_f32_e32 v4, v88, v59
	s_waitcnt vmcnt(27)
	v_pk_fma_f32 v[20:21], v[90:91], v[42:43], v[20:21] op_sel_hi:[0,1,1]
	s_waitcnt lgkmcnt(0)
	v_fmac_f32_e32 v4, v90, v60
	s_waitcnt vmcnt(26)
	v_pk_fma_f32 v[20:21], v[92:93], v[52:53], v[20:21] op_sel_hi:[0,1,1]
	v_fmac_f32_e32 v4, v92, v61
	s_waitcnt vmcnt(25)
	v_pk_fma_f32 v[20:21], v[94:95], v[44:45], v[20:21] op_sel_hi:[0,1,1]
	v_fmac_f32_e32 v4, v94, v62
	s_waitcnt vmcnt(24)
	v_pk_fma_f32 v[20:21], v[96:97], v[54:55], v[20:21] op_sel_hi:[0,1,1]
	v_fmac_f32_e32 v4, v96, v63
	v_lshl_add_u64 v[40:41], v[18:19], 0, s[22:23]
	global_load_dword v82, v[40:41], off
	v_add_co_u32_e32 v42, vcc, s76, v40
	s_nop 1
	v_addc_co_u32_e32 v43, vcc, 0, v41, vcc
	global_load_dword v84, v[42:43], off
	v_add_co_u32_e32 v42, vcc, s77, v40
	s_nop 1
	v_addc_co_u32_e32 v43, vcc, 0, v41, vcc
	global_load_dword v86, v[42:43], off
	v_add_co_u32_e32 v42, vcc, s63, v40
	s_nop 1
	v_addc_co_u32_e32 v43, vcc, 0, v41, vcc
	global_load_dword v88, v[42:43], off
	v_add_co_u32_e32 v42, vcc, s78, v40
	s_nop 1
	v_addc_co_u32_e32 v43, vcc, 0, v41, vcc
	global_load_dword v90, v[42:43], off
	v_add_co_u32_e32 v42, vcc, s79, v40
	s_nop 1
	v_addc_co_u32_e32 v43, vcc, 0, v41, vcc
	global_load_dword v92, v[42:43], off
	v_add_co_u32_e32 v42, vcc, s80, v40
	s_nop 1
	v_addc_co_u32_e32 v43, vcc, 0, v41, vcc
	global_load_dword v94, v[42:43], off
	v_add_co_u32_e32 v42, vcc, s81, v40
	s_nop 1
	v_addc_co_u32_e32 v43, vcc, 0, v41, vcc
	global_load_dword v96, v[42:43], off
	s_add_u32 s22, s22, 0x30000
	s_cmp_lg_u32 s22, 0x600000
	s_cselect_b32 s22, s22, 0
	ds_read_b128 v[40:43], v13
	ds_read_b128 v[44:47], v13 offset:16
	ds_read_b128 v[48:51], v13 offset:4096
	ds_read_b128 v[52:55], v13 offset:4112
	ds_read_b128 v[56:59], v13 offset:8192
	ds_read_b128 v[60:63], v13 offset:8208
	s_waitcnt lgkmcnt(5)
	v_mov_b32_e32 v80, v40
	s_waitcnt lgkmcnt(3)
; DI void phase0(const Params& p, unsigned char* smem, int bid, int nb) {
;     ...
; #pragma unroll 8
;       for (int k = 0; k < 256; ++k) {
;         const float w = wp[(size_t)k * 6144];
;         a0 += sc[kg * 256 + k] * w; a1 += sc[1024 + kg * 256 + k] * w; a2 += sc[2048 + kg * 256 + k] * w;
;       }
;       red[(kg * 3 + 0) * 64 + j] = a0; red[(kg * 3 + 1) * 64 + j] = a1; red[(kg * 3 + 2) * 64 + j] = a2;
;       __syncthreads();
;       if (tid < 192) {
;         const int cond = tid >> 6, jj = tid & 63;
;         float s = p.b_mod[l * 6144 + col0 + jj];
; #pragma unroll
;         for (int g = 0; g < 4; ++g) s += red[(g * 3 + cond) * 64 + jj];
;         p.mod[(l * 3 + cond) * 6144 + col0 + jj] = s;
;       }
	v_mov_b32_e32 v81, v48
	v_mov_b32_e32 v48, v41
	v_mov_b32_e32 v40, v42
	v_mov_b32_e32 v41, v50
	v_mov_b32_e32 v50, v43
	v_mov_b32_e32 v42, v44
	s_waitcnt lgkmcnt(2)
	v_mov_b32_e32 v43, v52
	v_mov_b32_e32 v52, v45
	v_mov_b32_e32 v44, v46
	v_mov_b32_e32 v45, v54
	v_mov_b32_e32 v54, v47
	v_add_u32_e32 v13, 32, v13
	s_waitcnt vmcnt(31)
	v_pk_fma_f32 v[20:21], v[100:101], v[80:81], v[20:21] op_sel_hi:[0,1,1]
	s_waitcnt lgkmcnt(1)
	v_fmac_f32_e32 v4, v100, v56
	s_waitcnt vmcnt(30)
	v_pk_fma_f32 v[20:21], v[102:103], v[48:49], v[20:21] op_sel_hi:[0,1,1]
	v_fmac_f32_e32 v4, v102, v57
	s_waitcnt vmcnt(29)
	v_pk_fma_f32 v[20:21], v[104:105], v[40:41], v[20:21] op_sel_hi:[0,1,1]
	v_fmac_f32_e32 v4, v104, v58
	s_waitcnt vmcnt(28)
	v_pk_fma_f32 v[20:21], v[106:107], v[50:51], v[20:21] op_sel_hi:[0,1,1]
	v_fmac_f32_e32 v4, v106, v59
	s_waitcnt vmcnt(27)
	v_pk_fma_f32 v[20:21], v[108:109], v[42:43], v[20:21] op_sel_hi:[0,1,1]
	s_waitcnt lgkmcnt(0)
	v_fmac_f32_e32 v4, v108, v60
	s_waitcnt vmcnt(26)
	v_pk_fma_f32 v[20:21], v[110:111], v[52:53], v[20:21] op_sel_hi:[0,1,1]
	v_fmac_f32_e32 v4, v110, v61
	s_waitcnt vmcnt(25)
	v_pk_fma_f32 v[20:21], v[112:113], v[44:45], v[20:21] op_sel_hi:[0,1,1]
	v_fmac_f32_e32 v4, v112, v62
	s_waitcnt vmcnt(24)
	v_pk_fma_f32 v[20:21], v[114:115], v[54:55], v[20:21] op_sel_hi:[0,1,1]
	v_fmac_f32_e32 v4, v114, v63
	v_lshl_add_u64 v[40:41], v[18:19], 0, s[22:23]
	global_load_dword v100, v[40:41], off
	v_add_co_u32_e32 v42, vcc, s76, v40
	s_nop 1
	v_addc_co_u32_e32 v43, vcc, 0, v41, vcc
	global_load_dword v102, v[42:43], off
	v_add_co_u32_e32 v42, vcc, s77, v40
	s_nop 1
	v_addc_co_u32_e32 v43, vcc, 0, v41, vcc
	global_load_dword v104, v[42:43], off
	v_add_co_u32_e32 v42, vcc, s63, v40
	s_nop 1
	v_addc_co_u32_e32 v43, vcc, 0, v41, vcc
	global_load_dword v106, v[42:43], off
	v_add_co_u32_e32 v42, vcc, s78, v40
	s_nop 1
	v_addc_co_u32_e32 v43, vcc, 0, v41, vcc
	global_load_dword v108, v[42:43], off
	v_add_co_u32_e32 v42, vcc, s79, v40
	s_nop 1
	v_addc_co_u32_e32 v43, vcc, 0, v41, vcc
	global_load_dword v110, v[42:43], off
	v_add_co_u32_e32 v42, vcc, s80, v40
	s_nop 1
	v_addc_co_u32_e32 v43, vcc, 0, v41, vcc
	global_load_dword v112, v[42:43], off
	v_add_co_u32_e32 v42, vcc, s81, v40
	s_nop 1
	v_addc_co_u32_e32 v43, vcc, 0, v41, vcc
	global_load_dword v114, v[42:43], off
	s_add_u32 s22, s22, 0x30000
	s_cmp_lg_u32 s22, 0x600000
	s_cselect_b32 s22, s22, 0
	ds_read_b128 v[40:43], v13
	ds_read_b128 v[44:47], v13 offset:16
	ds_read_b128 v[48:51], v13 offset:4096
	ds_read_b128 v[52:55], v13 offset:4112
	ds_read_b128 v[56:59], v13 offset:8192
	ds_read_b128 v[60:63], v13 offset:8208
	s_waitcnt lgkmcnt(5)
	v_mov_b32_e32 v80, v40
	s_waitcnt lgkmcnt(3)
	v_mov_b32_e32 v81, v48
	v_mov_b32_e32 v48, v41
	v_mov_b32_e32 v40, v42
	v_mov_b32_e32 v41, v50
	v_mov_b32_e32 v50, v43
	v_mov_b32_e32 v42, v44
	s_waitcnt lgkmcnt(2)
	v_mov_b32_e32 v43, v52
	v_mov_b32_e32 v52, v45
	v_mov_b32_e32 v44, v46
	v_mov_b32_e32 v45, v54
	v_mov_b32_e32 v54, v47
	v_add_u32_e32 v13, 32, v13
	s_waitcnt vmcnt(31)
	v_pk_fma_f32 v[20:21], v[118:119], v[80:81], v[20:21] op_sel_hi:[0,1,1]
	s_waitcnt lgkmcnt(1)
	v_fmac_f32_e32 v4, v118, v56
	s_waitcnt vmcnt(30)
	v_pk_fma_f32 v[20:21], v[120:121], v[48:49], v[20:21] op_sel_hi:[0,1,1]
	v_fmac_f32_e32 v4, v120, v57
	s_waitcnt vmcnt(29)
	v_pk_fma_f32 v[20:21], v[122:123], v[40:41], v[20:21] op_sel_hi:[0,1,1]
	v_fmac_f32_e32 v4, v122, v58
	s_waitcnt vmcnt(28)
	v_pk_fma_f32 v[20:21], v[124:125], v[50:51], v[20:21] op_sel_hi:[0,1,1]
	v_fmac_f32_e32 v4, v124, v59
	s_waitcnt vmcnt(27)
	v_pk_fma_f32 v[20:21], v[126:127], v[42:43], v[20:21] op_sel_hi:[0,1,1]
	s_waitcnt lgkmcnt(0)
	v_fmac_f32_e32 v4, v126, v60
	s_waitcnt vmcnt(26)
	v_pk_fma_f32 v[20:21], v[128:129], v[52:53], v[20:21] op_sel_hi:[0,1,1]
	v_fmac_f32_e32 v4, v128, v61
	s_waitcnt vmcnt(25)
	v_pk_fma_f32 v[20:21], v[130:131], v[44:45], v[20:21] op_sel_hi:[0,1,1]
	v_fmac_f32_e32 v4, v130, v62
	s_waitcnt vmcnt(24)
	v_pk_fma_f32 v[20:21], v[132:133], v[54:55], v[20:21] op_sel_hi:[0,1,1]
	v_fmac_f32_e32 v4, v132, v63
	s_add_i32 s17, s17, 1
	s_cmp_eq_u32 s17, 8
	s_cbranch_scc0 .LBB0_40
	s_waitcnt vmcnt(0)
	ds_write2st64_b32 v22, v20, v21 offset0:48 offset1:49
	ds_write_b32 v22, v4 offset:12800
	s_waitcnt lgkmcnt(0)
	s_barrier
	s_and_saveexec_b64 s[20:21], s[6:7]
	s_cbranch_execz .LBB0_13
	s_mul_i32 s17, s16, 0x1800
	s_add_i32 s17, s17, s18
	v_or_b32_e32 v18, s17, v8
	v_ashrrev_i32_e32 v19, 31, v18
	v_lshl_add_u64 v[18:19], v[18:19], 2, s[50:51]
	global_load_dword v4, v[18:19], off
	ds_read2st64_b32 v[18:19], v30 offset0:51 offset1:54
	ds_read_b32 v13, v29 offset:12288
	ds_read_b32 v15, v30 offset:14592
	v_mad_u64_u32 v[20:21], s[16:17], s16, 3, v[6:7]
	v_mul_lo_u32 v17, v20, s82
	v_add_u32_e32 v17, s18, v17
	v_or_b32_e32 v20, v17, v8
	v_ashrrev_i32_e32 v21, 31, v20
	s_waitcnt vmcnt(0) lgkmcnt(1)
	v_add_f32_e32 v4, v4, v13
	v_add_f32_e32 v4, v4, v18
	v_add_f32_e32 v4, v4, v19
	s_waitcnt lgkmcnt(0)
	v_add_f32_e32 v4, v4, v15
	v_lshl_add_u64 v[18:19], v[20:21], 2, s[52:53]
	global_store_dword v[18:19], v4, off
	s_branch .LBB0_13
